# mLSTM: transposed state accumulators (4 b64 state-copy writes), gate prefix in registers at commit, stage 0 + its barrier removed from steady state
# speedup vs baseline: 1.0381x; 1.0289x over previous
.LBB0_803:
	s_or_b64 exec, exec, s[18:19]
	s_mul_hi_i32 s18, s21, 0x2080000
	s_mul_i32 s21, s21, 0x2080000
	s_add_u32 s19, s12, s21
	s_addc_u32 s18, s13, s18
	s_lshl_b32 s21, s22, 1
	v_and_b32_e32 v84, 15, v110
	s_add_u32 s14, s14, s21
	v_lshlrev_b32_e32 v85, 1, v110
	s_addc_u32 s15, s15, 0
	s_lshl_b32 s20, s20, 4
	v_lshl_or_b32 v93, v111, 4, v84
	v_lshrrev_b32_e32 v86, 4, v82
	v_and_b32_e32 v88, 0xffffff80, v85
	s_add_u32 s62, s14, s20
	v_lshlrev_b32_e32 v85, 2, v82
	v_and_b32_e32 v82, 48, v82
	v_mul_lo_u32 v94, v93, s51
	s_addc_u32 s63, s15, 0
	v_readlane_b32 s24, v255, 4
	s_add_i32 s23, 0, 0x10a00
	v_add3_u32 v137, 0, v94, v82
	v_lshlrev_b32_e32 v94, 2, v93
	v_lshlrev_b32_e32 v141, 9, v86
	v_lshlrev_b32_e32 v89, 1, v84
	v_add_u32_e32 v132, s24, v85
	v_add_u32_e32 v133, s88, v85
	v_add_u32_e32 v134, s23, v85
	v_mul_u32_u24_e32 v92, 0x210, v84
	v_mad_u32_u24 v85, v84, s51, 0
	v_lshlrev_b32_e32 v135, 3, v86
	v_add_u32_e32 v139, s23, v94
	v_add_u32_e32 v95, 0, v141
	s_movk_i32 s23, 0xfe10
	v_mul_i32_i24_e32 v84, 0xfffffe40, v84
	v_add_u32_e32 v136, v85, v82
	v_add_u32_e32 v142, v95, v94
	v_mad_i32_i24 v95, v86, s23, v95
	v_add3_u32 v143, v85, v84, v135
	s_add_i32 s23, 0, 0x10200
	v_and_b32_e32 v85, 7, v110
	s_add_i32 s22, 0, 0x10b80
	v_add_u32_e32 v144, s23, v94
	v_ashrrev_i32_e32 v84, 3, v110
	v_lshlrev_b32_e32 v94, 5, v85
	v_add_lshl_u32 v94, v94, v84, 2
	s_add_u32 s19, s19, s21
	v_add_u32_e32 v145, s23, v94
	v_add_u32_e32 v146, 0, v94
	v_lshlrev_b32_e32 v94, 2, v84
	s_addc_u32 s21, s18, 0
	v_lshlrev_b32_e32 v87, 2, v86
	v_add_u32_e32 v96, s23, v94
	v_add_u32_e32 v148, 0, v94
	v_add_u32_e32 v149, s24, v94
	v_sub_u32_e32 v94, 31, v84
	s_add_u32 s18, s19, s20
	v_cndmask_b32_e64 v150, v94, v84, s[4:5]
	s_addc_u32 s19, s21, 0
	v_lshlrev_b32_e32 v84, 1, v85
	v_mov_b32_e32 v85, v17
	v_add_u32_e32 v154, s88, v82
	v_or_b32_e32 v82, 16, v87
	v_lshl_add_u64 v[84:85], s[18:19], 0, v[84:85]
	s_mov_b64 s[18:19], 0x6aa8000
	v_cmp_le_i32_e64 s[36:37], v82, v93
	v_lshl_add_u32 v158, v82, 2, s88
	v_or_b32_e32 v82, 17, v87
	v_lshl_add_u64 v[106:107], v[84:85], 0, s[18:19]
	s_movk_i32 s18, 0x1070
	v_cmp_le_i32_e64 s[38:39], v82, v93
	v_lshl_add_u32 v159, v82, 2, s88
	v_or_b32_e32 v82, 18, v87
	s_waitcnt lgkmcnt(0)
	v_mad_u32_u24 v84, v86, s18, v95
	v_lshl_add_u32 v153, v83, 4, s22
	v_or_b32_e32 v83, 1, v87
	v_cmp_le_i32_e64 s[40:41], v82, v93
	v_lshl_add_u32 v160, v82, 2, s88
	v_or_b32_e32 v82, 19, v87
	v_add3_u32 v90, 0, v88, v89
	v_and_b32_e32 v91, 31, v110
	v_lshl_add_u32 v151, v86, 5, s88
	v_add3_u32 v152, v84, v88, v89
	v_bfe_u32 v178, v119, 4, 2
	v_bfe_u32 v179, v119, 2, 2
	v_lshl_add_u32 v178, v178, 3, v179
	v_mul_u32_u24_e32 v178, 0x210, v178
	v_and_b32_e32 v179, 3, v119
	v_lshl_add_u32 v178, v179, 3, v178
	v_lshrrev_b32_e32 v179, 6, v119
	v_lshl_add_u32 v178, v179, 7, v178
	v_and_b32_e32 v179, 15, v119
	v_mul_u32_u24_e32 v179, 0x210, v179
	v_lshrrev_b32_e32 v196, 6, v119
	v_lshl_add_u32 v179, v196, 7, v179
	v_bfe_u32 v196, v119, 4, 2
	v_lshl_add_u32 v179, v196, 3, v179
	v_lshl_add_u64 v[108:109], s[16:17], 0, v[16:17]
	v_mul_u32_u24_e32 v16, 0x840, v86
	v_mul_u32_u24_e32 v84, 0x210, v83
	v_or_b32_e32 v85, 2, v87
	v_or_b32_e32 v86, 3, v87
	v_cmp_le_i32_e64 s[42:43], v82, v93
	v_lshl_add_u32 v161, v82, 2, s88
	v_mov_b32_e32 v82, 0
	v_cmp_gt_u32_e64 s[12:13], 64, v110
	v_lshl_add_u32 v131, v91, 4, s22
	v_cmp_lt_i32_e64 s[14:15], 1, v111
	v_add_u32_e32 v138, 0xffffbe00, v137
	v_add_u32_e32 v140, 0xffffff80, v139
	v_add_u32_e32 v147, 0x400, v96
	s_mov_b32 s52, 0
	v_cmp_eq_u32_e64 s[16:17], 0, v91
	v_cmp_gt_u32_e64 s[18:19], 2, v91
	v_cmp_gt_u32_e64 s[20:21], 4, v91
	v_cmp_gt_u32_e64 s[22:23], 8, v91
	v_cmp_gt_u32_e64 s[24:25], 16, v91
	v_cmp_le_i32_e64 s[26:27], v87, v93
	v_cmp_lt_i32_e64 s[28:29], v87, v93
	v_lshl_add_u32 v155, v83, 2, s88
	v_cmp_le_i32_e64 s[30:31], v85, v93
	v_lshl_add_u32 v156, v85, 2, s88
	v_cmp_le_i32_e64 s[34:35], v86, v93
	v_lshl_add_u32 v157, v86, 2, s88
	v_lshlrev_b32_e32 v162, 7, v83
	v_lshlrev_b32_e32 v163, 7, v85
	v_lshlrev_b32_e32 v164, 7, v86
	v_add_u32_e32 v165, v90, v16
	v_add_u32_e32 v166, v90, v84
	v_add_u32_e32 v167, v95, v92
	s_mov_b32 s77, 0
	v_mov_b32_e32 v83, v82
	v_mov_b32_e32 v84, v82
	v_mov_b32_e32 v85, v82
	v_mov_b32_e32 v86, v82
	v_mov_b32_e32 v87, v82
	v_mov_b32_e32 v88, v82
	v_mov_b32_e32 v89, v82
	v_mov_b32_e32 v90, v82
	v_mov_b32_e32 v91, v82
	v_mov_b32_e32 v92, v82
	v_mov_b32_e32 v93, v82
	v_mov_b32_e32 v94, v82
	v_mov_b32_e32 v95, v82
	v_mov_b32_e32 v96, v82
	v_mov_b32_e32 v97, v82
	s_barrier
	v_cndmask_b32_e64 v155, 0, v228, s[8:9]
	v_cndmask_b32_e64 v156, 0, v228, s[8:9]
	v_cndmask_b32_e64 v157, 0, v228, s[8:9]
	v_cndmask_b32_e64 v158, 0, v228, s[8:9]
	v_cndmask_b32_e64 v159, 0, v228, s[8:9]
	v_cndmask_b32_e64 v160, 0, v228, s[8:9]
	v_cndmask_b32_e64 v161, 0, v228, s[8:9]
	v_cndmask_b32_e64 v177, 0, v228, s[8:9]
	v_add_u32_e32 v155, v155, v122
	v_add_u32_e32 v156, v156, v123
	v_add_u32_e32 v157, v157, v124
	v_add_u32_e32 v158, v158, v125
	v_add_u32_e32 v159, v159, v126
	v_add_u32_e32 v160, v160, v127
	v_add_u32_e32 v161, v161, v128
	v_add_u32_e32 v177, v177, v129
	s_branch .LBB0_806
.LBB0_804:
	s_or_b64 exec, exec, s[44:45]
	v_cvt_pk_bf16_f32 v196, v94, v95
	v_cvt_pk_bf16_f32 v197, v96, v97
	ds_write_b64 v179, v[196:197] offset:55552
	v_cvt_pk_bf16_f32 v198, v90, v91
	v_cvt_pk_bf16_f32 v199, v92, v93
	ds_write_b64 v179, v[198:199] offset:55584
	v_cvt_pk_bf16_f32 v200, v86, v87
	v_cvt_pk_bf16_f32 v201, v88, v89
	ds_write_b64 v179, v[200:201] offset:55616
	v_cvt_pk_bf16_f32 v202, v82, v83
	v_cvt_pk_bf16_f32 v203, v84, v85
	ds_write_b64 v179, v[202:203] offset:55648

.LBB0_810:
	v_add_u32_e32 v168, 0xf800, v142
	s_cmp_lg_u32 s77, 0
	s_cbranch_scc1 .Lm1_s0skip
	s_and_saveexec_b64 s[44:45], s[12:13]
	s_cbranch_execz .LBB0_813
	ds_read_b128 v[98:101], v131
	s_waitcnt lgkmcnt(0)
	v_mov_b32_e32 v16, v98
	s_nop 1
	v_add_f32_dpp v16, v16, v16 row_shr:1 row_mask:0xf bank_mask:0xf bound_ctrl:1
	s_nop 1
	v_add_f32_dpp v16, v16, v16 row_shr:2 row_mask:0xf bank_mask:0xf bound_ctrl:1
	s_nop 1
	v_add_f32_dpp v16, v16, v16 row_shr:4 row_mask:0xf bank_mask:0xf bound_ctrl:1
	s_nop 1
	v_add_f32_dpp v16, v16, v16 row_shr:8 row_mask:0xf bank_mask:0xf bound_ctrl:1
	s_nop 1
	v_add_f32_dpp v16, v16, v16 row_bcast:15 row_mask:0xa bank_mask:0xf
	s_and_b64 exec, exec, s[6:7]
	s_cbranch_execz .LBB0_813
	v_sub_f32_e32 v98, v99, v16
	ds_write_b32 v134, v16
	ds_write_b32 v133, v98
	ds_write_b32 v132, v100
.LBB0_813:
	s_or_b64 exec, exec, s[44:45]
	v_cvt_pk_bf16_f32 v196, v94, v95
	v_cvt_pk_bf16_f32 v197, v96, v97
	ds_write_b64 v179, v[196:197] offset:55552
	v_cvt_pk_bf16_f32 v198, v90, v91
	v_cvt_pk_bf16_f32 v199, v92, v93
	ds_write_b64 v179, v[198:199] offset:55584
	v_cvt_pk_bf16_f32 v200, v86, v87
	v_cvt_pk_bf16_f32 v201, v88, v89
	ds_write_b64 v179, v[200:201] offset:55616
	v_cvt_pk_bf16_f32 v202, v82, v83
	v_cvt_pk_bf16_f32 v203, v84, v85
	ds_write_b64 v179, v[202:203] offset:55648
	s_waitcnt lgkmcnt(0)
	s_barrier
.Lm1_s0skip:
	s_and_saveexec_b64 s[44:45], s[14:15]
	s_xor_b64 s[44:45], exec, s[44:45]
	s_cbranch_execz .Lm1_w01
	ds_read_b32 v16, v140
	ds_read_b128 v[180:183], v136 offset:55552
	ds_read_b128 v[184:187], v138
	ds_read_b128 v[188:191], v136 offset:55616
	ds_read_b128 v[192:195], v138 offset:64
	ds_read_b128 v[196:199], v136 offset:55680
	ds_read_b128 v[200:203], v138 offset:128
	ds_read_b128 v[204:207], v136 offset:55744
	ds_read_b128 v[212:215], v138 offset:192
	ds_read_b128 v[216:219], v136 offset:55808
	ds_read_b128 v[220:223], v138 offset:256
	ds_read_b128 v[230:233], v136 offset:55872
	ds_read_b128 v[234:237], v138 offset:320
	ds_read_b128 v[244:247], v136 offset:55936
	ds_read_b128 v[248:251], v138 offset:384
	s_waitcnt lgkmcnt(12)
	v_mul_f32_e32 v16, 0x3fb8aa3b, v16
	v_mfma_f32_16x16x32_bf16 v[98:101], v[180:183], v[184:187], 0
	ds_read_b128 v[180:183], v136 offset:56000
	ds_read_b128 v[184:187], v138 offset:448
	v_exp_f32_e32 v16, v16
	s_waitcnt lgkmcnt(12)
	v_mfma_f32_16x16x32_bf16 v[98:101], v[188:191], v[192:195], v[98:101]
	s_waitcnt lgkmcnt(10)
	v_mfma_f32_16x16x32_bf16 v[98:101], v[196:199], v[200:203], v[98:101]
	s_waitcnt lgkmcnt(8)
	v_mfma_f32_16x16x32_bf16 v[98:101], v[204:207], v[212:215], v[98:101]
	s_waitcnt lgkmcnt(6)
	v_mfma_f32_16x16x32_bf16 v[98:101], v[216:219], v[220:223], v[98:101]
	s_waitcnt lgkmcnt(4)
	v_mfma_f32_16x16x32_bf16 v[98:101], v[230:233], v[234:237], v[98:101]
	s_waitcnt lgkmcnt(2)
	v_mfma_f32_16x16x32_bf16 v[98:101], v[244:247], v[248:251], v[98:101]
	s_waitcnt lgkmcnt(0)
	v_mfma_f32_16x16x32_bf16 v[98:101], v[180:183], v[184:187], v[98:101]
	s_nop 7
	v_mul_f32_e32 v98, v98, v16
	v_mul_f32_e32 v99, v99, v16
	v_mul_f32_e32 v100, v100, v16
	v_mul_f32_e32 v101, v101, v16
	ds_write2_b32 v168, v98, v99 offset0:96 offset1:128
	ds_write2_b32 v168, v100, v101 offset0:160 offset1:192

.LBB0_829:
	s_or_b64 exec, exec, s[44:45]
	v_sub_co_u32_e64 v16, s[44:45], s77, 8
	s_waitcnt lgkmcnt(14)
	v_mov_b32_e32 v98, s77
	s_and_b64 s[74:75], s[44:45], exec
	v_cndmask_b32_e64 v16, v16, v98, s[44:45]
	s_cselect_b32 s78, 7, 0x1ff
	v_sub_u32_e32 v98, s78, v16
	v_cndmask_b32_e64 v16, v98, v16, s[4:5]
	s_waitcnt lgkmcnt(0)
	s_barrier
	ds_read_b32 v216, v145
	ds_read_b32 v217, v146 offset:64000
	ds_read_b32 v218, v147
	ds_read_b32 v219, v148 offset:65024
	ds_read_b32 v220, v149
	s_cselect_b32 s74, 0x4000, 0
	v_add_u32_e32 v169, s74, v150
	v_add_u32_e32 v170, v143, v135
	v_lshl_add_u32 v222, v16, 5, v169
	v_mov_b32_e32 v221, s89
	ds_read_b32 v171, v221
	ds_read_b128 v[98:101], v170 offset:54272
	ds_read_b128 v[102:105], v151
	ds_read_b128 v[172:175], v151 offset:16
	s_waitcnt lgkmcnt(4)
	v_add_f32_e32 v216, v216, v217
	v_add_f32_e32 v218, v218, v219
	v_max_f32_e32 v220, v220, v220
	v_max_f32_e64 v218, |v218|, v220
	v_rcp_f32_e32 v218, v218
	v_ashrrev_i32_e32 v223, 31, v222
	v_lshlrev_b64 v[222:223], 11, v[222:223]
	v_mul_f32_e32 v216, v216, v218
	v_lshl_add_u64 v[222:223], v[106:107], 0, v[222:223]
	v_cvt_pk_bf16_f32 v220, v216, v17
	global_store_short v[222:223], v220, off
	ds_read_b64_tr_b16 v[180:181], v178 offset:16896
	ds_read_b64_tr_b16 v[182:183], v178 offset:19008
	ds_read_b64_tr_b16 v[184:185], v178 offset:16928
	ds_read_b64_tr_b16 v[186:187], v178 offset:19040
	ds_read_b64_tr_b16 v[188:189], v178 offset:16960
	ds_read_b64_tr_b16 v[190:191], v178 offset:19072
	ds_read_b64_tr_b16 v[192:193], v178 offset:16992
	ds_read_b64_tr_b16 v[194:195], v178 offset:19104
	s_waitcnt lgkmcnt(8)
	v_lshlrev_b32_e32 v176, 16, v98
	v_add_f32_e32 v103, v171, v103
	v_mul_f32_e32 v103, 0x3fb8aa3b, v103
	v_exp_f32_e32 v103, v103
	v_add_f32_e32 v102, v171, v102
	v_mul_f32_e32 v102, 0x3fb8aa3b, v102
	v_and_b32_e32 v98, 0xffff0000, v98
	v_exp_f32_e32 v102, v102
	v_mul_f32_e32 v98, v103, v98
	v_add_f32_e32 v103, v171, v104
	v_mul_f32_e32 v103, 0x3fb8aa3b, v103
	v_exp_f32_e32 v103, v103
	v_mul_f32_e32 v102, v102, v176
	v_cvt_pk_bf16_f32 v98, v102, v98
	v_lshlrev_b32_e32 v102, 16, v99
	v_mul_f32_e32 v102, v103, v102
	v_add_f32_e32 v103, v171, v105
	v_mul_f32_e32 v103, 0x3fb8aa3b, v103
	v_exp_f32_e32 v103, v103
	v_and_b32_e32 v99, 0xffff0000, v99
	v_mul_f32_e32 v16, 0x3fb8aa3b, v171
	v_exp_f32_e32 v16, v16
	v_mul_f32_e32 v99, v103, v99
	v_add_f32_e32 v103, v171, v172
	v_mul_f32_e32 v103, 0x3fb8aa3b, v103
	v_exp_f32_e32 v103, v103
	v_cvt_pk_bf16_f32 v99, v102, v99
	v_lshlrev_b32_e32 v102, 16, v100
	v_and_b32_e32 v100, 0xffff0000, v100
	v_mul_f32_e32 v102, v103, v102
	v_add_f32_e32 v103, v171, v173
	v_mul_f32_e32 v103, 0x3fb8aa3b, v103
	v_exp_f32_e32 v103, v103
	v_pk_mul_f32 v[96:97], v[96:97], v[16:17] op_sel_hi:[1,0]
	v_pk_mul_f32 v[94:95], v[94:95], v[16:17] op_sel_hi:[1,0]
	v_pk_mul_f32 v[92:93], v[92:93], v[16:17] op_sel_hi:[1,0]
	v_mul_f32_e32 v100, v103, v100
	v_add_f32_e32 v103, v171, v174
	v_mul_f32_e32 v103, 0x3fb8aa3b, v103
	v_exp_f32_e32 v103, v103
	v_cvt_pk_bf16_f32 v100, v102, v100
	v_lshlrev_b32_e32 v102, 16, v101
	v_and_b32_e32 v101, 0xffff0000, v101
	v_mul_f32_e32 v102, v103, v102
	v_add_f32_e32 v103, v171, v175
	v_mul_f32_e32 v103, 0x3fb8aa3b, v103
	v_exp_f32_e32 v103, v103
	v_pk_mul_f32 v[90:91], v[90:91], v[16:17] op_sel_hi:[1,0]
	v_pk_mul_f32 v[88:89], v[88:89], v[16:17] op_sel_hi:[1,0]
	v_pk_mul_f32 v[86:87], v[86:87], v[16:17] op_sel_hi:[1,0]
	v_mul_f32_e32 v101, v103, v101
	v_cvt_pk_bf16_f32 v101, v102, v101
	v_pk_mul_f32 v[84:85], v[84:85], v[16:17] op_sel_hi:[1,0]
	v_pk_mul_f32 v[82:83], v[82:83], v[16:17] op_sel_hi:[1,0]
	s_waitcnt lgkmcnt(0)
	s_barrier
	s_nop 1
	v_mfma_f32_16x16x32_bf16 v[94:97], v[180:183], v[98:101], v[94:97]
	v_mfma_f32_16x16x32_bf16 v[90:93], v[184:187], v[98:101], v[90:93]
	v_mfma_f32_16x16x32_bf16 v[86:89], v[188:191], v[98:101], v[86:89]
	v_mfma_f32_16x16x32_bf16 v[82:85], v[192:195], v[98:101], v[82:85]
	s_waitcnt vmcnt(8)
	ds_write_b128 v155, v[46:49]
	s_waitcnt vmcnt(7)
	ds_write_b128 v156, v[50:53]
	s_waitcnt vmcnt(6)
	ds_write_b128 v157, v[54:57]
	s_waitcnt vmcnt(5)
	ds_write_b128 v158, v[58:61]
	s_waitcnt vmcnt(4)
	ds_write_b128 v159, v[66:69]
	s_waitcnt vmcnt(3)
	ds_write_b128 v160, v[70:73]
	s_waitcnt vmcnt(2)
	ds_write_b128 v161, v[74:77]
	s_waitcnt vmcnt(1)
	ds_write_b128 v177, v[78:81]
	s_and_saveexec_b64 s[74:75], s[10:11]
	s_cbranch_execz .LBB0_847
.LBB0_846:
	s_waitcnt vmcnt(1)
	v_mov_b32_e32 v16, v26
	s_and_b64 vcc, exec, s[4:5]
	s_cbranch_vccz .Lmg_rev0
	s_nop 1
	v_add_f32_dpp v16, v16, v16 row_shr:1 row_mask:0xf bank_mask:0xf bound_ctrl:1
	s_nop 1
	v_add_f32_dpp v16, v16, v16 row_shr:2 row_mask:0xf bank_mask:0xf bound_ctrl:1
	s_nop 1
	v_add_f32_dpp v16, v16, v16 row_shr:4 row_mask:0xf bank_mask:0xf bound_ctrl:1
	s_nop 1
	v_add_f32_dpp v16, v16, v16 row_shr:8 row_mask:0xf bank_mask:0xf bound_ctrl:1
	s_nop 1
	v_add_f32_dpp v16, v16, v16 row_bcast:15 row_mask:0xa bank_mask:0xf
	s_branch .Lmg_done0
.Lmg_rev0:
	s_nop 1
	v_add_f32_dpp v16, v16, v16 row_shl:1 row_mask:0xf bank_mask:0xf bound_ctrl:1
	s_nop 1
	v_add_f32_dpp v16, v16, v16 row_shl:2 row_mask:0xf bank_mask:0xf bound_ctrl:1
	s_nop 1
	v_add_f32_dpp v16, v16, v16 row_shl:4 row_mask:0xf bank_mask:0xf bound_ctrl:1
	s_nop 1
	v_add_f32_dpp v16, v16, v16 row_shl:8 row_mask:0xf bank_mask:0xf bound_ctrl:1
	s_nop 1
	v_readlane_b32 vcc_lo, v16, 16
	s_mov_b64 exec, 0xffff
	s_nop 0
	v_add_f32_e32 v16, vcc_lo, v16
	s_mov_b32 exec_lo, -1
	s_mov_b32 exec_hi, 0
.Lmg_done0:
	s_nop 0
	v_sub_f32_e32 v204, v27, v16
	v_lshrrev_b32_e32 v205, 2, v153
	ds_write_b32 v205, v16 offset:50976
	ds_write_b32 v205, v204 offset:51104
	ds_write_b32 v205, v28 offset:51232
	ds_write_b16 v130, v62 offset:54272
	ds_write_b16_d16_hi v130, v62 offset:54352
	ds_write_b16 v130, v63 offset:54432
	ds_write_b16_d16_hi v130, v63 offset:54512
	ds_write_b16 v130, v64 offset:54592
	ds_write_b16_d16_hi v130, v64 offset:54672
	ds_write_b16 v130, v65 offset:54752
	ds_write_b16_d16_hi v130, v65 offset:54832
	ds_write_b16 v130, v211 offset:54912
.LBB0_847:
	s_or_b64 exec, exec, s[74:75]
	v_cvt_pk_bf16_f32 v196, v94, v95
	v_cvt_pk_bf16_f32 v197, v96, v97
	ds_write_b64 v179, v[196:197] offset:55552
	v_cvt_pk_bf16_f32 v198, v90, v91
	v_cvt_pk_bf16_f32 v199, v92, v93
	ds_write_b64 v179, v[198:199] offset:55584
	v_cvt_pk_bf16_f32 v200, v86, v87
	v_cvt_pk_bf16_f32 v201, v88, v89
	ds_write_b64 v179, v[200:201] offset:55616
	v_cvt_pk_bf16_f32 v202, v82, v83
	v_cvt_pk_bf16_f32 v203, v84, v85
	ds_write_b64 v179, v[202:203] offset:55648
	s_waitcnt lgkmcnt(0)
	s_andn2_b64 vcc, exec, s[58:59]
	s_barrier
	s_cbranch_vccnz .LBB0_851
	s_cmp_lt_u32 s77, 6
	s_cselect_b32 s58, 2, -6
	s_cselect_b32 s59, 7, 0x1ff
	s_cselect_b32 s74, 0x4000, 0
	s_add_i32 s75, s58, s77
	s_sub_i32 s58, s59, s58
	s_add_i32 s58, s52, s58
	s_add_i32 s75, s75, 1
	s_add_i32 s79, s58, -1
	s_and_b64 s[58:59], s[4:5], exec
	s_cselect_b32 s58, s75, s79
	s_lshl_b32 s58, s58, 5
	s_add_i32 s74, s58, s74
	s_waitcnt vmcnt(8)
	v_add_u32_e32 v46, s74, v111
	v_add_u32_e32 v48, s74, v112
	s_waitcnt vmcnt(6)
	v_add_u32_e32 v54, s74, v113
	v_add_u32_e32 v56, s74, v114
	s_waitcnt vmcnt(4)
	v_add_u32_e32 v66, s74, v115
	v_add_u32_e32 v68, s74, v116
	s_waitcnt vmcnt(2)
	v_add_u32_e32 v74, s74, v117
	v_add_u32_e32 v76, s74, v121
	v_ashrrev_i32_e32 v47, 31, v46
	v_ashrrev_i32_e32 v49, 31, v48
	v_ashrrev_i32_e32 v55, 31, v54
	v_ashrrev_i32_e32 v57, 31, v56
	v_ashrrev_i32_e32 v67, 31, v66
	v_ashrrev_i32_e32 v69, 31, v68
	v_ashrrev_i32_e32 v75, 31, v74
	v_ashrrev_i32_e32 v77, 31, v76
	v_lshlrev_b64 v[46:47], 12, v[46:47]
	v_lshlrev_b64 v[48:49], 12, v[48:49]
	v_lshlrev_b64 v[54:55], 12, v[54:55]
	v_lshlrev_b64 v[56:57], 12, v[56:57]
	v_lshlrev_b64 v[66:67], 12, v[66:67]
	v_lshlrev_b64 v[68:69], 12, v[68:69]
	v_lshlrev_b64 v[74:75], 12, v[74:75]
	v_lshlrev_b64 v[76:77], 12, v[76:77]
	v_lshl_add_u64 v[46:47], v[108:109], 0, v[46:47]
	v_lshl_add_u64 v[50:51], v[108:109], 0, v[48:49]
	v_lshl_add_u64 v[54:55], v[108:109], 0, v[54:55]
	v_lshl_add_u64 v[58:59], v[108:109], 0, v[56:57]
	v_lshl_add_u64 v[66:67], v[108:109], 0, v[66:67]
	v_lshl_add_u64 v[70:71], v[108:109], 0, v[68:69]
	v_lshl_add_u64 v[74:75], v[108:109], 0, v[74:75]
	s_waitcnt vmcnt(1)
	v_lshl_add_u64 v[78:79], v[108:109], 0, v[76:77]
	global_load_dwordx4 v[46:49], v[46:47], off
	s_nop 0
	global_load_dwordx4 v[50:53], v[50:51], off
	s_nop 0
	global_load_dwordx4 v[54:57], v[54:55], off
	s_nop 0
	global_load_dwordx4 v[58:61], v[58:59], off
	s_nop 0
	global_load_dwordx4 v[66:69], v[66:67], off
	s_nop 0
	global_load_dwordx4 v[70:73], v[70:71], off
	s_nop 0
	global_load_dwordx4 v[74:77], v[74:75], off
	s_nop 0
	global_load_dwordx4 v[78:81], v[78:79], off
	s_and_saveexec_b64 s[58:59], s[10:11]
	s_cbranch_execz .LBB0_850
	v_add_u32_e32 v26, s74, v110
	v_ashrrev_i32_e32 v27, 31, v26
	v_lshl_add_u64 v[28:29], v[26:27], 4, s[48:49]
	v_lshlrev_b64 v[26:27], 11, v[26:27]
	v_lshl_add_u64 v[26:27], s[62:63], 0, v[26:27]
	global_load_dwordx4 v[62:65], v[26:27], off
	s_nop 0
	global_load_dwordx4 v[26:29], v[28:29], off

.LBB0_851:
	s_and_saveexec_b64 s[58:59], s[14:15]
	s_xor_b64 s[58:59], exec, s[58:59]
	s_cbranch_execz .Lm2_w01
	ds_read_b32 v16, v140
	ds_read_b128 v[180:183], v136 offset:55552
	ds_read_b128 v[184:187], v138
	ds_read_b128 v[188:191], v136 offset:55616
	ds_read_b128 v[192:195], v138 offset:64
	ds_read_b128 v[196:199], v136 offset:55680
	ds_read_b128 v[200:203], v138 offset:128
	ds_read_b128 v[204:207], v136 offset:55744
	ds_read_b128 v[212:215], v138 offset:192
	ds_read_b128 v[216:219], v136 offset:55808
	ds_read_b128 v[220:223], v138 offset:256
	ds_read_b128 v[230:233], v136 offset:55872
	ds_read_b128 v[234:237], v138 offset:320
	ds_read_b128 v[244:247], v136 offset:55936
	ds_read_b128 v[248:251], v138 offset:384
	s_waitcnt lgkmcnt(12)
	v_mul_f32_e32 v16, 0x3fb8aa3b, v16
	v_mfma_f32_16x16x32_bf16 v[98:101], v[180:183], v[184:187], 0
	ds_read_b128 v[180:183], v136 offset:56000
	ds_read_b128 v[184:187], v138 offset:448
	v_exp_f32_e32 v16, v16
	s_waitcnt lgkmcnt(12)
	v_mfma_f32_16x16x32_bf16 v[98:101], v[188:191], v[192:195], v[98:101]
	s_waitcnt lgkmcnt(10)
	v_mfma_f32_16x16x32_bf16 v[98:101], v[196:199], v[200:203], v[98:101]
	s_waitcnt lgkmcnt(8)
	v_mfma_f32_16x16x32_bf16 v[98:101], v[204:207], v[212:215], v[98:101]
	s_waitcnt lgkmcnt(6)
	v_mfma_f32_16x16x32_bf16 v[98:101], v[216:219], v[220:223], v[98:101]
	s_waitcnt lgkmcnt(4)
	v_mfma_f32_16x16x32_bf16 v[98:101], v[230:233], v[234:237], v[98:101]
	s_waitcnt lgkmcnt(2)
	v_mfma_f32_16x16x32_bf16 v[98:101], v[244:247], v[248:251], v[98:101]
	s_waitcnt lgkmcnt(0)
	v_mfma_f32_16x16x32_bf16 v[98:101], v[180:183], v[184:187], v[98:101]
	s_nop 7
	v_mul_f32_e32 v98, v98, v16
	v_mul_f32_e32 v99, v99, v16
	v_mul_f32_e32 v100, v100, v16
	v_mul_f32_e32 v101, v101, v16
	ds_write2_b32 v168, v98, v99 offset0:96 offset1:128
	ds_write2_b32 v168, v100, v101 offset0:160 offset1:192

.LBB0_870:
	s_or_b64 exec, exec, s[58:59]
	s_waitcnt lgkmcnt(0)
	s_barrier
	ds_read_b32 v216, v145
	ds_read_b32 v217, v146 offset:64000
	ds_read_b32 v218, v147
	ds_read_b32 v219, v148 offset:65024
	ds_read_b32 v220, v149
	s_add_i32 s58, s77, 1
	s_add_i32 s59, s77, -7
	s_and_b64 s[44:45], s[44:45], exec
	s_cselect_b32 s59, s58, s59
	s_sub_i32 s74, s78, s59
	s_and_b64 s[44:45], s[4:5], exec
	s_cselect_b32 s44, s59, s74
	s_cmpk_gt_u32 s58, 0x206
	v_lshl_add_u32 v222, s44, 5, v169
	v_mov_b32_e32 v221, s89
	ds_read_b32 v172, v221
	ds_read_b128 v[98:101], v170 offset:54272
	ds_read_b128 v[102:105], v151
	ds_read_b128 v[168:171], v151 offset:16
	s_waitcnt lgkmcnt(4)
	v_add_f32_e32 v216, v216, v217
	v_add_f32_e32 v218, v218, v219
	v_max_f32_e32 v220, v220, v220
	v_max_f32_e64 v218, |v218|, v220
	v_rcp_f32_e32 v218, v218
	v_ashrrev_i32_e32 v223, 31, v222
	v_lshlrev_b64 v[222:223], 11, v[222:223]
	v_mul_f32_e32 v216, v216, v218
	v_lshl_add_u64 v[222:223], v[106:107], 0, v[222:223]
	v_cvt_pk_bf16_f32 v220, v216, v17
	global_store_short v[222:223], v220, off
	ds_read_b64_tr_b16 v[180:181], v178 offset:16896
	ds_read_b64_tr_b16 v[182:183], v178 offset:19008
	ds_read_b64_tr_b16 v[184:185], v178 offset:16928
	ds_read_b64_tr_b16 v[186:187], v178 offset:19040
	ds_read_b64_tr_b16 v[188:189], v178 offset:16960
	ds_read_b64_tr_b16 v[190:191], v178 offset:19072
	ds_read_b64_tr_b16 v[192:193], v178 offset:16992
	ds_read_b64_tr_b16 v[194:195], v178 offset:19104
	s_waitcnt lgkmcnt(8)
	v_lshlrev_b32_e32 v173, 16, v98
	v_add_f32_e32 v103, v172, v103
	v_mul_f32_e32 v103, 0x3fb8aa3b, v103
	v_exp_f32_e32 v103, v103
	v_add_f32_e32 v102, v172, v102
	v_mul_f32_e32 v102, 0x3fb8aa3b, v102
	v_and_b32_e32 v98, 0xffff0000, v98
	v_exp_f32_e32 v102, v102
	v_mul_f32_e32 v98, v103, v98
	v_add_f32_e32 v103, v172, v104
	v_mul_f32_e32 v103, 0x3fb8aa3b, v103
	v_exp_f32_e32 v103, v103
	v_mul_f32_e32 v102, v102, v173
	v_cvt_pk_bf16_f32 v98, v102, v98
	v_lshlrev_b32_e32 v102, 16, v99
	v_mul_f32_e32 v102, v103, v102
	v_add_f32_e32 v103, v172, v105
	v_mul_f32_e32 v103, 0x3fb8aa3b, v103
	v_exp_f32_e32 v103, v103
	v_and_b32_e32 v99, 0xffff0000, v99
	v_mul_f32_e32 v16, 0x3fb8aa3b, v172
	v_exp_f32_e32 v16, v16
	v_mul_f32_e32 v99, v103, v99
	v_add_f32_e32 v103, v172, v168
	v_mul_f32_e32 v103, 0x3fb8aa3b, v103
	v_exp_f32_e32 v103, v103
	v_cvt_pk_bf16_f32 v99, v102, v99
	v_lshlrev_b32_e32 v102, 16, v100
	v_and_b32_e32 v100, 0xffff0000, v100
	v_mul_f32_e32 v102, v103, v102
	v_add_f32_e32 v103, v172, v169
	v_mul_f32_e32 v103, 0x3fb8aa3b, v103
	v_exp_f32_e32 v103, v103
	v_pk_mul_f32 v[96:97], v[96:97], v[16:17] op_sel_hi:[1,0]
	v_pk_mul_f32 v[94:95], v[94:95], v[16:17] op_sel_hi:[1,0]
	v_pk_mul_f32 v[92:93], v[92:93], v[16:17] op_sel_hi:[1,0]
	v_mul_f32_e32 v100, v103, v100
	v_add_f32_e32 v103, v172, v170
	v_mul_f32_e32 v103, 0x3fb8aa3b, v103
	v_exp_f32_e32 v103, v103
	v_cvt_pk_bf16_f32 v100, v102, v100
	v_lshlrev_b32_e32 v102, 16, v101
	v_and_b32_e32 v101, 0xffff0000, v101
	v_mul_f32_e32 v102, v103, v102
	v_add_f32_e32 v103, v172, v171
	v_mul_f32_e32 v103, 0x3fb8aa3b, v103
	v_exp_f32_e32 v103, v103
	v_pk_mul_f32 v[90:91], v[90:91], v[16:17] op_sel_hi:[1,0]
	v_pk_mul_f32 v[88:89], v[88:89], v[16:17] op_sel_hi:[1,0]
	v_pk_mul_f32 v[86:87], v[86:87], v[16:17] op_sel_hi:[1,0]
	v_mul_f32_e32 v101, v103, v101
	v_cvt_pk_bf16_f32 v101, v102, v101
	v_pk_mul_f32 v[84:85], v[84:85], v[16:17] op_sel_hi:[1,0]
	v_pk_mul_f32 v[82:83], v[82:83], v[16:17] op_sel_hi:[1,0]
	s_waitcnt lgkmcnt(0)
	s_barrier
	s_nop 1
	v_mfma_f32_16x16x32_bf16 v[94:97], v[180:183], v[98:101], v[94:97]
	v_mfma_f32_16x16x32_bf16 v[90:93], v[184:187], v[98:101], v[90:93]
	v_mfma_f32_16x16x32_bf16 v[86:89], v[188:191], v[98:101], v[86:89]
	v_mfma_f32_16x16x32_bf16 v[82:85], v[192:195], v[98:101], v[82:85]
	s_cbranch_scc1 .LBB0_805
	s_waitcnt vmcnt(9)
	ds_write_b128 v155, v[0:3]
	s_waitcnt vmcnt(8)
	ds_write_b128 v156, v[4:7]
	s_waitcnt vmcnt(7)
	ds_write_b128 v157, v[8:11]
	s_waitcnt vmcnt(6)
	ds_write_b128 v158, v[12:15]
	s_waitcnt vmcnt(5)
	ds_write_b128 v159, v[22:25]
	s_waitcnt vmcnt(4)
	ds_write_b128 v160, v[30:33]
	s_waitcnt vmcnt(3)
	ds_write_b128 v161, v[38:41]
	s_waitcnt vmcnt(2)
	ds_write_b128 v177, v[42:45]
	s_and_saveexec_b64 s[44:45], s[10:11]
	s_cbranch_execz .LBB0_804
	s_branch .LBB0_928
.LBB0_928:
	s_waitcnt vmcnt(2)
	v_mov_b32_e32 v16, v34
	s_and_b64 vcc, exec, s[4:5]
	s_cbranch_vccz .Lmg_rev1
	s_nop 1
	v_add_f32_dpp v16, v16, v16 row_shr:1 row_mask:0xf bank_mask:0xf bound_ctrl:1
	s_nop 1
	v_add_f32_dpp v16, v16, v16 row_shr:2 row_mask:0xf bank_mask:0xf bound_ctrl:1
	s_nop 1
	v_add_f32_dpp v16, v16, v16 row_shr:4 row_mask:0xf bank_mask:0xf bound_ctrl:1
	s_nop 1
	v_add_f32_dpp v16, v16, v16 row_shr:8 row_mask:0xf bank_mask:0xf bound_ctrl:1
	s_nop 1
	v_add_f32_dpp v16, v16, v16 row_bcast:15 row_mask:0xa bank_mask:0xf
	s_branch .Lmg_done1

.Lmg_done1:
	s_nop 0
	v_sub_f32_e32 v204, v35, v16
	v_lshrrev_b32_e32 v205, 2, v153
	ds_write_b32 v205, v16 offset:50976
	ds_write_b32 v205, v204 offset:51104
	ds_write_b32 v205, v36 offset:51232
	ds_write_b16 v130, v18 offset:54272
	ds_write_b16_d16_hi v130, v18 offset:54352
	ds_write_b16 v130, v19 offset:54432
	ds_write_b16_d16_hi v130, v19 offset:54512
	ds_write_b16 v130, v20 offset:54592
	ds_write_b16_d16_hi v130, v20 offset:54672
	ds_write_b16 v130, v21 offset:54752
	ds_write_b16_d16_hi v130, v21 offset:54832
	ds_write_b16 v130, v211 offset:54912
	s_branch .LBB0_804
